# speedup vs baseline: 1.0162x; 1.0037x over previous
; __device__ __forceinline__ unsigned cvt_pk_bf16(float lo, float hi) { const f32x2 v = {lo, hi}; const bf16x2_t b = __builtin_convertvector(v, bf16x2_t); return __builtin_bit_cast(unsigned, b); }
; __device__ __forceinline__ void softmax_pv(f32x16& s0, f32x16& s1, float& mref, f32x16& negm, float& lsum, f32x16 (&o)[2], LAS float* fac, const bf16x8 (&vf)[2][4], bool first, int r32, int hi) {
;     ...
;     float ps0 = 0.f, ps1 = 0.f;
; #pragma unroll
;     for (int r = 0; r < 16; ++r) { s0[r] = __builtin_amdgcn_exp2f(s0[r]); s1[r] = __builtin_amdgcn_exp2f(s1[r]); ps0 += s0[r]; ps1 += s1[r]; }
;     lsum += ps0 + ps1;
;     bf16x8 pa[4];
; #pragma unroll
;     for (int k = 0; k < 4; ++k) {
;         const f32x16& s = (k < 2) ? s0 : s1; const int rb = 8 * (k & 1);
;         u32x4 w; w.x = cvt_pk_bf16(s[rb + 0], s[rb + 1]); w.y = cvt_pk_bf16(s[rb + 2], s[rb + 3]); w.z = cvt_pk_bf16(s[rb + 4], s[rb + 5]); w.w = cvt_pk_bf16(s[rb + 6], s[rb + 7]);
;         pa[k] = __builtin_bit_cast(bf16x8, w);
;     }
; #pragma unroll
;     for (int k = 0; k < 4; ++k) {
;         o[0] = __builtin_amdgcn_mfma_f32_32x32x16_bf16(pa[k], vf[0][k], o[0], 0, 0, 0);
;         o[1] = __builtin_amdgcn_mfma_f32_32x32x16_bf16(pa[k], vf[1][k], o[1], 0, 0, 0);
;     }
.Ldr_cont_00:
	v_exp_f32_e32 v80, v80
	v_exp_f32_e32 v81, v81
	v_exp_f32_e32 v82, v82
	v_exp_f32_e32 v83, v83
	v_exp_f32_e32 v84, v84
	v_exp_f32_e32 v85, v85
	v_exp_f32_e32 v86, v86
	v_exp_f32_e32 v87, v87
	v_cvt_pk_bf16_f32 v210, v80, v81
	v_cvt_pk_bf16_f32 v211, v82, v83
	v_cvt_pk_bf16_f32 v212, v84, v85
	v_cvt_pk_bf16_f32 v213, v86, v87
	v_mfma_f32_4x4x4_16b_bf16 v[164:167], v[210:211], v[214:215], v[164:167]
	v_exp_f32_e32 v88, v88
	v_exp_f32_e32 v89, v89
	v_mfma_f32_4x4x4_16b_bf16 v[164:167], v[212:213], v[214:215], v[164:167]
	v_exp_f32_e32 v90, v90
	v_exp_f32_e32 v91, v91
	v_mfma_f32_32x32x16_bf16 v[32:47], v[210:213], v[128:131], v[32:47]
	v_exp_f32_e32 v92, v92
	v_exp_f32_e32 v93, v93
	v_exp_f32_e32 v94, v94
	v_exp_f32_e32 v95, v95
	v_mfma_f32_32x32x16_bf16 v[48:63], v[210:213], v[144:147], v[48:63]
	v_cvt_pk_bf16_f32 v248, v88, v89
	v_cvt_pk_bf16_f32 v249, v90, v91
	v_cvt_pk_bf16_f32 v250, v92, v93
	v_cvt_pk_bf16_f32 v251, v94, v95
	v_mfma_f32_4x4x4_16b_bf16 v[164:167], v[248:249], v[214:215], v[164:167]
	v_exp_f32_e32 v64, v64
	v_exp_f32_e32 v65, v65
	v_mfma_f32_4x4x4_16b_bf16 v[164:167], v[250:251], v[214:215], v[164:167]
	v_exp_f32_e32 v66, v66
	v_exp_f32_e32 v67, v67
	s_waitcnt lgkmcnt(12)
	v_mfma_f32_32x32x16_bf16 v[32:47], v[248:251], v[132:135], v[32:47]
	v_exp_f32_e32 v68, v68
	v_exp_f32_e32 v69, v69
	v_mfma_f32_32x32x16_bf16 v[48:63], v[248:251], v[148:151], v[48:63]
	s_waitcnt lgkmcnt(8)
	v_mfma_f32_32x32x16_bf16 v[80:95], v[234:237], v[120:123], v[218:233]
	v_exp_f32_e32 v70, v70
	v_exp_f32_e32 v71, v71
	v_mfma_f32_32x32x16_bf16 v[80:95], v[242:245], v[124:127], v[80:95]
	v_cvt_pk_bf16_f32 v210, v64, v65
	v_cvt_pk_bf16_f32 v211, v66, v67
	v_cvt_pk_bf16_f32 v212, v68, v69
	v_cvt_pk_bf16_f32 v213, v70, v71
	v_mfma_f32_4x4x4_16b_bf16 v[164:167], v[210:211], v[214:215], v[164:167]
	v_exp_f32_e32 v72, v72
	v_exp_f32_e32 v73, v73
	v_mfma_f32_4x4x4_16b_bf16 v[164:167], v[212:213], v[214:215], v[164:167]
	v_exp_f32_e32 v74, v74
	v_exp_f32_e32 v75, v75
	s_waitcnt lgkmcnt(4)
	v_mfma_f32_32x32x16_bf16 v[32:47], v[210:213], v[136:139], v[32:47]
	v_exp_f32_e32 v76, v76
	v_exp_f32_e32 v77, v77
	v_exp_f32_e32 v78, v78
	v_exp_f32_e32 v79, v79
	v_mfma_f32_32x32x16_bf16 v[48:63], v[210:213], v[152:155], v[48:63]
	v_cvt_pk_bf16_f32 v248, v72, v73
	v_cvt_pk_bf16_f32 v249, v74, v75
	v_cvt_pk_bf16_f32 v250, v76, v77
	v_cvt_pk_bf16_f32 v251, v78, v79
	v_mfma_f32_4x4x4_16b_bf16 v[164:167], v[248:249], v[214:215], v[164:167]
	s_nop 1
	v_mfma_f32_4x4x4_16b_bf16 v[164:167], v[250:251], v[214:215], v[164:167]
	v_mfma_f32_32x32x16_bf16 v[64:79], v[238:241], v[120:123], v[218:233]
	v_mfma_f32_32x32x16_bf16 v[64:79], v[188:191], v[124:127], v[64:79]
	s_waitcnt lgkmcnt(0)
	v_mfma_f32_32x32x16_bf16 v[32:47], v[248:251], v[140:143], v[32:47]
	v_mfma_f32_32x32x16_bf16 v[48:63], v[248:251], v[156:159], v[48:63]
	ds_read_b128 v[234:237], v187 offset:20480
	ds_read_b128 v[238:241], v187 offset:20992
	ds_read_b128 v[242:245], v187 offset:22528
	ds_read_b128 v[188:191], v187 offset:23040
	s_cmp_eq_u32 s34, 0
	s_cbranch_scc1 .Ldr_first_01
.Ldr_cont_01:
	v_exp_f32_e32 v80, v80
	v_exp_f32_e32 v81, v81
	v_exp_f32_e32 v82, v82
	v_exp_f32_e32 v83, v83
	v_exp_f32_e32 v84, v84
	v_exp_f32_e32 v85, v85
	v_exp_f32_e32 v86, v86
	v_exp_f32_e32 v87, v87
	v_cvt_pk_bf16_f32 v210, v80, v81
	v_cvt_pk_bf16_f32 v211, v82, v83
	v_cvt_pk_bf16_f32 v212, v84, v85
	v_cvt_pk_bf16_f32 v213, v86, v87
	v_mfma_f32_4x4x4_16b_bf16 v[172:175], v[210:211], v[214:215], v[172:175]
	v_exp_f32_e32 v88, v88
	v_exp_f32_e32 v89, v89
	v_mfma_f32_4x4x4_16b_bf16 v[172:175], v[212:213], v[214:215], v[172:175]
	v_exp_f32_e32 v90, v90
	v_exp_f32_e32 v91, v91
	v_mfma_f32_32x32x16_bf16 v[0:15], v[210:213], v[128:131], v[0:15]
	v_exp_f32_e32 v92, v92
	v_exp_f32_e32 v93, v93
	v_exp_f32_e32 v94, v94
	v_exp_f32_e32 v95, v95
	v_mfma_f32_32x32x16_bf16 v[16:31], v[210:213], v[144:147], v[16:31]
	v_cvt_pk_bf16_f32 v248, v88, v89
	v_cvt_pk_bf16_f32 v249, v90, v91
	v_cvt_pk_bf16_f32 v250, v92, v93
	v_cvt_pk_bf16_f32 v251, v94, v95
	v_mfma_f32_4x4x4_16b_bf16 v[172:175], v[248:249], v[214:215], v[172:175]
	v_exp_f32_e32 v64, v64
	v_exp_f32_e32 v65, v65
	v_mfma_f32_4x4x4_16b_bf16 v[172:175], v[250:251], v[214:215], v[172:175]
	v_exp_f32_e32 v66, v66
	v_exp_f32_e32 v67, v67
	v_mfma_f32_32x32x16_bf16 v[0:15], v[248:251], v[132:135], v[0:15]
	v_exp_f32_e32 v68, v68
	v_exp_f32_e32 v69, v69
	v_mfma_f32_32x32x16_bf16 v[16:31], v[248:251], v[148:151], v[16:31]
	s_waitcnt lgkmcnt(0)
	v_mfma_f32_32x32x16_bf16 v[80:95], v[234:237], v[104:107], v[194:209]
	v_exp_f32_e32 v70, v70
	v_exp_f32_e32 v71, v71
	v_mfma_f32_32x32x16_bf16 v[80:95], v[242:245], v[112:115], v[80:95]
	v_cvt_pk_bf16_f32 v210, v64, v65
	v_cvt_pk_bf16_f32 v211, v66, v67
	v_cvt_pk_bf16_f32 v212, v68, v69
	v_cvt_pk_bf16_f32 v213, v70, v71
	v_mfma_f32_4x4x4_16b_bf16 v[172:175], v[210:211], v[214:215], v[172:175]
	v_exp_f32_e32 v72, v72
	v_exp_f32_e32 v73, v73
	v_mfma_f32_4x4x4_16b_bf16 v[172:175], v[212:213], v[214:215], v[172:175]
	v_exp_f32_e32 v74, v74
	v_exp_f32_e32 v75, v75
	v_mfma_f32_32x32x16_bf16 v[0:15], v[210:213], v[136:139], v[0:15]
	v_exp_f32_e32 v76, v76
	v_exp_f32_e32 v77, v77
	v_exp_f32_e32 v78, v78
	v_exp_f32_e32 v79, v79
	v_mfma_f32_32x32x16_bf16 v[16:31], v[210:213], v[152:155], v[16:31]
	v_cvt_pk_bf16_f32 v248, v72, v73
	v_cvt_pk_bf16_f32 v249, v74, v75
	v_cvt_pk_bf16_f32 v250, v76, v77
	v_cvt_pk_bf16_f32 v251, v78, v79
	v_mfma_f32_4x4x4_16b_bf16 v[172:175], v[248:249], v[214:215], v[172:175]
	s_nop 1
	v_mfma_f32_4x4x4_16b_bf16 v[172:175], v[250:251], v[214:215], v[172:175]
	v_mfma_f32_32x32x16_bf16 v[64:79], v[238:241], v[104:107], v[194:209]
	v_mfma_f32_32x32x16_bf16 v[64:79], v[188:191], v[112:115], v[64:79]
	v_mfma_f32_32x32x16_bf16 v[0:15], v[248:251], v[140:143], v[0:15]
	v_mfma_f32_32x32x16_bf16 v[16:31], v[248:251], v[156:159], v[16:31]
	ds_read_b128 v[234:237], v187 offset:24576
	ds_read_b128 v[238:241], v187 offset:25088
	ds_read_b128 v[242:245], v187 offset:26624
	ds_read_b128 v[188:191], v187 offset:27136
	ds_read_b64_tr_b16 v[128:129], v163 offset:32768
	ds_read_b64_tr_b16 v[130:131], v163 offset:33280
	ds_read_b64_tr_b16 v[144:145], v163 offset:36864
	ds_read_b64_tr_b16 v[146:147], v163 offset:37376
	ds_read_b64_tr_b16 v[132:133], v163 offset:33792
	ds_read_b64_tr_b16 v[134:135], v163 offset:34304
	ds_read_b64_tr_b16 v[148:149], v163 offset:37888
	ds_read_b64_tr_b16 v[150:151], v163 offset:38400
	s_waitcnt lgkmcnt(7)
; __device__ __forceinline__ unsigned cvt_pk_bf16(float lo, float hi) { const f32x2 v = {lo, hi}; const bf16x2_t b = __builtin_convertvector(v, bf16x2_t); return __builtin_bit_cast(unsigned, b); }
; __device__ __forceinline__ s16x4 vtr(const LAS unsigned char* p) { return __builtin_bit_cast(s16x4, __builtin_amdgcn_ds_read_tr16_b64_v4i16((LAS s16x4*)p)); }
; __device__ __forceinline__ void softmax_pv(f32x16& s0, f32x16& s1, float& mref, f32x16& negm, float& lsum, f32x16 (&o)[2], LAS float* fac, const bf16x8 (&vf)[2][4], bool first, int r32, int hi) {
;     ...
;     float ps0 = 0.f, ps1 = 0.f;
; #pragma unroll
;     for (int r = 0; r < 16; ++r) { s0[r] = __builtin_amdgcn_exp2f(s0[r]); s1[r] = __builtin_amdgcn_exp2f(s1[r]); ps0 += s0[r]; ps1 += s1[r]; }
;     lsum += ps0 + ps1;
;     bf16x8 pa[4];
; #pragma unroll
;     for (int k = 0; k < 4; ++k) {
;         const f32x16& s = (k < 2) ? s0 : s1; const int rb = 8 * (k & 1);
;         u32x4 w; w.x = cvt_pk_bf16(s[rb + 0], s[rb + 1]); w.y = cvt_pk_bf16(s[rb + 2], s[rb + 3]); w.z = cvt_pk_bf16(s[rb + 4], s[rb + 5]); w.w = cvt_pk_bf16(s[rb + 6], s[rb + 7]);
;         pa[k] = __builtin_bit_cast(bf16x8, w);
;     }
; #pragma unroll
;     for (int k = 0; k < 4; ++k) {
;         o[0] = __builtin_amdgcn_mfma_f32_32x32x16_bf16(pa[k], vf[0][k], o[0], 0, 0, 0);
;         o[1] = __builtin_amdgcn_mfma_f32_32x32x16_bf16(pa[k], vf[1][k], o[1], 0, 0, 0);
;     }
; template <bool DIFF>
; __device__ __forceinline__ void attn_item(const Params& p, int l, int I, LAS unsigned char* lds, const int tid) {
;     ...
;         for (int dh = 0; dh < 2; ++dh)
; #pragma unroll
;             for (int k = 0; k < 4; ++k) { const s16x4 lo = vtr(vb + dh * 4096 + k * 1024), hh = vtr(vb + dh * 4096 + k * 1024 + 512);
;                 vf[dh][k] = (bf16x8){lo[0], lo[1], lo[2], lo[3], hh[0], hh[1], hh[2], hh[3]}; }
	ds_read_b64_tr_b16 v[136:137], v163 offset:34816
	ds_read_b64_tr_b16 v[138:139], v163 offset:35328
	ds_read_b64_tr_b16 v[152:153], v163 offset:38912
	ds_read_b64_tr_b16 v[154:155], v163 offset:39424
	ds_read_b64_tr_b16 v[140:141], v163 offset:35840
	ds_read_b64_tr_b16 v[142:143], v163 offset:36352
	ds_read_b64_tr_b16 v[156:157], v163 offset:39936
	ds_read_b64_tr_b16 v[158:159], v163 offset:40448
	v_exp_f32_e32 v80, v80
	v_exp_f32_e32 v81, v81
	v_exp_f32_e32 v82, v82
	v_exp_f32_e32 v83, v83
	v_exp_f32_e32 v84, v84
	v_exp_f32_e32 v85, v85
	v_exp_f32_e32 v86, v86
	v_exp_f32_e32 v87, v87
	v_cvt_pk_bf16_f32 v210, v80, v81
	v_cvt_pk_bf16_f32 v211, v82, v83
	v_cvt_pk_bf16_f32 v212, v84, v85
	v_cvt_pk_bf16_f32 v213, v86, v87
	v_mfma_f32_4x4x4_16b_bf16 v[164:167], v[210:211], v[214:215], v[164:167]
	v_exp_f32_e32 v88, v88
	v_exp_f32_e32 v89, v89
	v_mfma_f32_4x4x4_16b_bf16 v[164:167], v[212:213], v[214:215], v[164:167]
	v_exp_f32_e32 v90, v90
	v_exp_f32_e32 v91, v91
	s_waitcnt lgkmcnt(12)
	v_mfma_f32_32x32x16_bf16 v[32:47], v[210:213], v[128:131], v[32:47]
	v_exp_f32_e32 v92, v92
	v_exp_f32_e32 v93, v93
	v_exp_f32_e32 v94, v94
	v_exp_f32_e32 v95, v95
	v_mfma_f32_32x32x16_bf16 v[48:63], v[210:213], v[144:147], v[48:63]
	v_cvt_pk_bf16_f32 v248, v88, v89
	v_cvt_pk_bf16_f32 v249, v90, v91
	v_cvt_pk_bf16_f32 v250, v92, v93
	v_cvt_pk_bf16_f32 v251, v94, v95
	v_mfma_f32_4x4x4_16b_bf16 v[164:167], v[248:249], v[214:215], v[164:167]
	v_exp_f32_e32 v64, v64
	v_exp_f32_e32 v65, v65
	v_mfma_f32_4x4x4_16b_bf16 v[164:167], v[250:251], v[214:215], v[164:167]
	v_exp_f32_e32 v66, v66
	v_exp_f32_e32 v67, v67
	s_waitcnt lgkmcnt(8)
	v_mfma_f32_32x32x16_bf16 v[32:47], v[248:251], v[132:135], v[32:47]
	v_exp_f32_e32 v68, v68
	v_exp_f32_e32 v69, v69
	v_mfma_f32_32x32x16_bf16 v[48:63], v[248:251], v[148:151], v[48:63]
	v_mfma_f32_32x32x16_bf16 v[80:95], v[234:237], v[120:123], v[218:233]
	v_exp_f32_e32 v70, v70
	v_exp_f32_e32 v71, v71
	v_mfma_f32_32x32x16_bf16 v[80:95], v[242:245], v[124:127], v[80:95]
	v_cvt_pk_bf16_f32 v210, v64, v65
	v_cvt_pk_bf16_f32 v211, v66, v67
	v_cvt_pk_bf16_f32 v212, v68, v69
	v_cvt_pk_bf16_f32 v213, v70, v71
	v_mfma_f32_4x4x4_16b_bf16 v[164:167], v[210:211], v[214:215], v[164:167]
	v_exp_f32_e32 v72, v72
	v_exp_f32_e32 v73, v73
	v_mfma_f32_4x4x4_16b_bf16 v[164:167], v[212:213], v[214:215], v[164:167]
	v_exp_f32_e32 v74, v74
	v_exp_f32_e32 v75, v75
	s_waitcnt lgkmcnt(4)
	v_mfma_f32_32x32x16_bf16 v[32:47], v[210:213], v[136:139], v[32:47]
	v_exp_f32_e32 v76, v76
	v_exp_f32_e32 v77, v77
	v_exp_f32_e32 v78, v78
	v_exp_f32_e32 v79, v79
	v_mfma_f32_32x32x16_bf16 v[48:63], v[210:213], v[152:155], v[48:63]
	v_cvt_pk_bf16_f32 v248, v72, v73
	v_cvt_pk_bf16_f32 v249, v74, v75
	v_cvt_pk_bf16_f32 v250, v76, v77
	v_cvt_pk_bf16_f32 v251, v78, v79
	v_mfma_f32_4x4x4_16b_bf16 v[164:167], v[248:249], v[214:215], v[164:167]
	s_nop 1
	v_mfma_f32_4x4x4_16b_bf16 v[164:167], v[250:251], v[214:215], v[164:167]
	v_mfma_f32_32x32x16_bf16 v[64:79], v[238:241], v[120:123], v[218:233]
	v_mfma_f32_32x32x16_bf16 v[64:79], v[188:191], v[124:127], v[64:79]
	s_waitcnt lgkmcnt(0)
	v_mfma_f32_32x32x16_bf16 v[32:47], v[248:251], v[140:143], v[32:47]
	v_mfma_f32_32x32x16_bf16 v[48:63], v[248:251], v[156:159], v[48:63]
	v_exp_f32_e32 v80, v80
	v_exp_f32_e32 v81, v81
	v_exp_f32_e32 v82, v82
	v_exp_f32_e32 v83, v83
	v_exp_f32_e32 v84, v84
	v_exp_f32_e32 v85, v85
	v_exp_f32_e32 v86, v86
	v_exp_f32_e32 v87, v87
	v_cvt_pk_bf16_f32 v210, v80, v81
	v_cvt_pk_bf16_f32 v211, v82, v83
	v_cvt_pk_bf16_f32 v212, v84, v85
	v_cvt_pk_bf16_f32 v213, v86, v87
	v_mfma_f32_4x4x4_16b_bf16 v[172:175], v[210:211], v[214:215], v[172:175]
	v_exp_f32_e32 v88, v88
	v_exp_f32_e32 v89, v89
	v_mfma_f32_4x4x4_16b_bf16 v[172:175], v[212:213], v[214:215], v[172:175]
	v_exp_f32_e32 v90, v90
	v_exp_f32_e32 v91, v91
	v_mfma_f32_32x32x16_bf16 v[0:15], v[210:213], v[128:131], v[0:15]
	v_exp_f32_e32 v92, v92
	v_exp_f32_e32 v93, v93
	v_exp_f32_e32 v94, v94
	v_exp_f32_e32 v95, v95
	v_mfma_f32_32x32x16_bf16 v[16:31], v[210:213], v[144:147], v[16:31]
	v_cvt_pk_bf16_f32 v248, v88, v89
	v_cvt_pk_bf16_f32 v249, v90, v91
	v_cvt_pk_bf16_f32 v250, v92, v93
	v_cvt_pk_bf16_f32 v251, v94, v95
	v_mfma_f32_4x4x4_16b_bf16 v[172:175], v[248:249], v[214:215], v[172:175]
	v_exp_f32_e32 v64, v64
	v_exp_f32_e32 v65, v65
	v_mfma_f32_4x4x4_16b_bf16 v[172:175], v[250:251], v[214:215], v[172:175]
	v_exp_f32_e32 v66, v66
	v_exp_f32_e32 v67, v67
	v_mfma_f32_32x32x16_bf16 v[0:15], v[248:251], v[132:135], v[0:15]
	v_exp_f32_e32 v68, v68
	v_exp_f32_e32 v69, v69
	v_exp_f32_e32 v70, v70
	v_exp_f32_e32 v71, v71
	v_mfma_f32_32x32x16_bf16 v[16:31], v[248:251], v[148:151], v[16:31]
	v_cvt_pk_bf16_f32 v210, v64, v65
	v_cvt_pk_bf16_f32 v211, v66, v67
	v_cvt_pk_bf16_f32 v212, v68, v69
	v_cvt_pk_bf16_f32 v213, v70, v71
	v_mfma_f32_4x4x4_16b_bf16 v[172:175], v[210:211], v[214:215], v[172:175]
	v_exp_f32_e32 v72, v72
	v_exp_f32_e32 v73, v73
	v_mfma_f32_4x4x4_16b_bf16 v[172:175], v[212:213], v[214:215], v[172:175]
	v_exp_f32_e32 v74, v74
	v_exp_f32_e32 v75, v75
	v_mfma_f32_32x32x16_bf16 v[0:15], v[210:213], v[136:139], v[0:15]
	v_exp_f32_e32 v76, v76
	v_exp_f32_e32 v77, v77
	v_exp_f32_e32 v78, v78
	v_exp_f32_e32 v79, v79
	v_mfma_f32_32x32x16_bf16 v[16:31], v[210:213], v[152:155], v[16:31]
	v_cvt_pk_bf16_f32 v248, v72, v73
	v_cvt_pk_bf16_f32 v249, v74, v75
	v_cvt_pk_bf16_f32 v250, v76, v77
	v_cvt_pk_bf16_f32 v251, v78, v79
	v_mfma_f32_4x4x4_16b_bf16 v[172:175], v[248:249], v[214:215], v[172:175]
	s_nop 1
	v_mfma_f32_4x4x4_16b_bf16 v[172:175], v[250:251], v[214:215], v[172:175]
	v_mfma_f32_32x32x16_bf16 v[0:15], v[248:251], v[140:143], v[0:15]
	v_mfma_f32_32x32x16_bf16 v[16:31], v[248:251], v[156:159], v[16:31]
	s_nop 5
	v_max3_f32 v210, v164, v165, v166
	v_max3_f32 v210, v210, v167, v172
	v_max3_f32 v210, v210, v173, v174
	v_max_f32_e32 v210, v210, v175
	v_cmp_lt_f32_e32 vcc, 0x47800000, v210
	s_cbranch_vccnz .Ldq
